# speedup vs baseline: 1.0067x; 1.0067x over previous
; #define PG8_STAGE(bufoff, gbase, voff) do { _Pragma("unroll") for (int _i = 0; _i < 2; ++_i) \
;         __builtin_amdgcn_global_load_lds((const unsigned*)((const char*)(gbase) + (voff)[_i]), (LAS unsigned*)(lds + (bufoff) + ldsw + _i * 8192), 16, 0, 0); } while (0)
; #define PG8_LDA(dst, b, h) do { _Pragma("unroll") for (int m = 0; m < 4; ++m) _Pragma("unroll") for (int k = 0; k < 2; ++k) dst[m][k] = *(const LAS bf16x8*)(lds + PG8_SA(b, h) + aoff + m * 2048 + k * 1024); } while (0)
; #define PG8_LDB(dst, b, h) do { _Pragma("unroll") for (int n = 0; n < 2; ++n) _Pragma("unroll") for (int k = 0; k < 2; ++k) dst[n][k] = *(const LAS bf16x8*)(lds + PG8_SB(b, h) + boff + n * 2048 + k * 1024); } while (0)
; #define PG8_SCHED __builtin_amdgcn_sched_barrier(0)
; __device__ __forceinline__ void gemm_phase(LAS unsigned char* lds, const GemmD& g) {
;     ...
;     f32x4 acc[2][2][4][2];
; #pragma unroll
;     for (int a = 0; a < 2; ++a)
; #pragma unroll
;         for (int b = 0; b < 2; ++b)
; #pragma unroll
;             for (int m = 0; m < 4; ++m)
; #pragma unroll
;                 for (int n = 0; n < 2; ++n) acc[a][b][m][n] = (f32x4){0.f, 0.f, 0.f, 0.f};
;     ...
;     for (;;) {
;         const bool has_next = unit_get(g, nM, nN, G, cblk, ui + 1, nxt);
;         const char* nA = has_next ? (const char*)g.A + (size_t)nxt.pm * tstep + (size_t)nxt.k0 * kstep : cA; const char* nB = has_next ? (const char*)g.Bt + (size_t)nxt.pn * tstep + (size_t)nxt.k0 * kstep : cB;
;         const int nt = cur.nt;
;         for (int t = 0; t < nt; t += 2) {
;             const bool last = (t == nt - 2);
;             const char* a1 = cA + (size_t)(t + 1) * kstep;
;             const char* a2 = last ? nA : cA + (size_t)(t + 2) * kstep; const char* b2 = last ? nB : cB + (size_t)(t + 2) * kstep;
;             const char* a3 = a2 + kstep; const char* b3 = b2 + kstep;
;             PG8_LDB(B0, 0, 0); PG8_SCHED; PG8_LDA(At, 0, 0); PG8_STAGE(PG8_SA(1, 1), a1 + hstep, voffA);
.LBB0_144:
	v_lshl_add_u64 v[132:133], v[2:3], 0, s[46:47]
	v_add_u32_e32 v135, -2, v134
	v_lshl_add_u64 v[130:131], v[4:5], 0, s[44:45]
	s_mov_b32 s4, 0
	s_waitcnt vmcnt(0)
	v_readfirstlane_b32 s98, v130
	v_readfirstlane_b32 s99, v131
	v_readfirstlane_b32 s100, v132
	v_readfirstlane_b32 s101, v133
	v_add_u32_e32 v242, s72, v172
	v_add_u32_e32 v243, s72, v168
	v_add_u32_e32 v244, 0x10000, v229
	v_add_u32_e32 v245, 0x14000, v229
	v_add_u32_e32 v246, 0x18000, v229
	v_add_u32_e32 v247, 0x1c000, v229
	s_add_i32 s6, 0, 0x10000
	ds_read_b128 v[136:139], v244
	ds_read_b128 v[140:143], v244 offset:1024
	ds_read_b128 v[144:147], v244 offset:2048
	ds_read_b128 v[148:151], v244 offset:3072
	v_cmp_eq_u32_e32 vcc, s4, v135
	s_add_i32 s5, s4, 2
	s_add_i32 m0, s2, 0xc000
	ds_read_b128 v[152:155], v233
	ds_read_b128 v[156:159], v233 offset:1024
	ds_read_b128 v[160:163], v233 offset:2048
	ds_read_b128 v[184:187], v233 offset:3072
	ds_read_b128 v[188:191], v233 offset:4096
	ds_read_b128 v[192:195], v233 offset:5120
	ds_read_b128 v[196:199], v233 offset:6144
	ds_read_b128 v[200:203], v233 offset:7168
	global_load_lds_dwordx4 v174, s[98:99]
	s_add_i32 m0, s2, 0xe000
	s_nop 0
	global_load_lds_dwordx4 v176, s[98:99]
	s_cbranch_vccz .Lkp_notlast
	v_readfirstlane_b32 s98, v180
	v_readfirstlane_b32 s99, v181
	v_readfirstlane_b32 s100, v182
	v_readfirstlane_b32 s101, v183
	s_branch .Lkp_ptr_done

; #define PG8_STAGE(bufoff, gbase, voff) do { _Pragma("unroll") for (int _i = 0; _i < 2; ++_i) \
;         __builtin_amdgcn_global_load_lds((const unsigned*)((const char*)(gbase) + (voff)[_i]), (LAS unsigned*)(lds + (bufoff) + ldsw + _i * 8192), 16, 0, 0); } while (0)
; #define PG8_LDA(dst, b, h) do { _Pragma("unroll") for (int m = 0; m < 4; ++m) _Pragma("unroll") for (int k = 0; k < 2; ++k) dst[m][k] = *(const LAS bf16x8*)(lds + PG8_SA(b, h) + aoff + m * 2048 + k * 1024); } while (0)
; #define PG8_LDB(dst, b, h) do { _Pragma("unroll") for (int n = 0; n < 2; ++n) _Pragma("unroll") for (int k = 0; k < 2; ++k) dst[n][k] = *(const LAS bf16x8*)(lds + PG8_SB(b, h) + boff + n * 2048 + k * 1024); } while (0)
; #define PG8_MMA(ai, bj, At, Bt) do { __builtin_amdgcn_s_setprio(1); _Pragma("unroll") for (int m = 0; m < 4; ++m) _Pragma("unroll") for (int n = 0; n < 2; ++n) _Pragma("unroll") for (int k = 0; k < 2; ++k) \
;         acc[ai][bj][m][n] = __builtin_amdgcn_mfma_f32_16x16x32_bf16(Bt[n][k], At[m][k], acc[ai][bj][m][n], 0, 0, 0); __builtin_amdgcn_s_setprio(0); } while (0)
; #define PG8_WAIT_V(n) asm volatile("s_waitcnt vmcnt(" #n ")" ::: "memory")
; #define PG8_WAIT_L(n) asm volatile("s_waitcnt lgkmcnt(" #n ")" ::: "memory")
; #define PG8_BAR __builtin_amdgcn_s_barrier()
; #define PG8_SCHED __builtin_amdgcn_sched_barrier(0)
; __device__ __forceinline__ void gemm_phase(LAS unsigned char* lds, const GemmD& g) {
;     ...
;             PG8_LDB(B0, 0, 0); PG8_SCHED; PG8_LDA(At, 0, 0); PG8_STAGE(PG8_SA(1, 1), a1 + hstep, voffA);
;             PG8_WAIT_L(8); PG8_BAR; PG8_WAIT_L(0); PG8_MMA(0, 0, At, B0); PG8_BAR; PG8_SCHED;
;             PG8_LDB(B1, 0, 1); PG8_STAGE(PG8_SB(0, 0), b2, voffB);
;             PG8_BAR; PG8_WAIT_L(0); PG8_MMA(0, 1, At, B1); PG8_BAR;
;             PG8_LDA(At, 0, 1); PG8_STAGE(PG8_SA(0, 0), a2, voffA);
;             PG8_BAR; PG8_WAIT_L(0); PG8_MMA(1, 0, At, B0); PG8_BAR; PG8_SCHED;
;             PG8_STAGE(PG8_SB(0, 1), b2 + hstep, voffB);
;             PG8_WAIT_V(6); PG8_BAR; PG8_MMA(1, 1, At, B1); PG8_BAR;
.Lkp_ptr_done:
	s_waitcnt lgkmcnt(8)
	s_barrier
	s_waitcnt lgkmcnt(0)
	v_mfma_f32_16x16x32_bf16 v[126:129], v[136:139], v[152:155], 0
	v_mfma_f32_16x16x32_bf16 v[122:125], v[144:147], v[152:155], 0
	v_mfma_f32_16x16x32_bf16 v[110:113], v[136:139], v[160:163], 0
	v_mfma_f32_16x16x32_bf16 v[106:109], v[144:147], v[160:163], 0
	v_mfma_f32_16x16x32_bf16 v[94:97], v[136:139], v[188:191], 0
	v_mfma_f32_16x16x32_bf16 v[90:93], v[144:147], v[188:191], 0
	v_mfma_f32_16x16x32_bf16 v[78:81], v[136:139], v[196:199], 0
	v_mfma_f32_16x16x32_bf16 v[74:77], v[144:147], v[196:199], 0
	v_mfma_f32_16x16x32_bf16 v[126:129], v[140:143], v[156:159], v[126:129]
	v_mfma_f32_16x16x32_bf16 v[122:125], v[148:151], v[156:159], v[122:125]
	v_mfma_f32_16x16x32_bf16 v[110:113], v[140:143], v[184:187], v[110:113]
	v_mfma_f32_16x16x32_bf16 v[106:109], v[148:151], v[184:187], v[106:109]
	v_mfma_f32_16x16x32_bf16 v[94:97], v[140:143], v[192:195], v[94:97]
	v_mfma_f32_16x16x32_bf16 v[90:93], v[148:151], v[192:195], v[90:93]
	v_mfma_f32_16x16x32_bf16 v[78:81], v[140:143], v[200:203], v[78:81]
	v_mfma_f32_16x16x32_bf16 v[74:77], v[148:151], v[200:203], v[74:77]
	s_barrier
	s_add_i32 s4, 0, 0x14000
	s_add_i32 s6, s6, s87
	s_mov_b32 m0, s6
	ds_read_b128 v[204:207], v245
	ds_read_b128 v[208:211], v245 offset:1024
	ds_read_b128 v[234:237], v245 offset:2048
	ds_read_b128 v[238:241], v245 offset:3072
	global_load_lds_dwordx4 v172, s[100:101]
	s_add_i32 m0, s6, 0x2000
	s_nop 0
	global_load_lds_dwordx4 v168, s[100:101]
	s_barrier
	s_waitcnt lgkmcnt(0)
	v_mfma_f32_16x16x32_bf16 v[118:121], v[204:207], v[152:155], 0
	v_mfma_f32_16x16x32_bf16 v[114:117], v[234:237], v[152:155], 0
	v_mfma_f32_16x16x32_bf16 v[102:105], v[204:207], v[160:163], 0
	v_mfma_f32_16x16x32_bf16 v[98:101], v[234:237], v[160:163], 0
	v_mfma_f32_16x16x32_bf16 v[86:89], v[204:207], v[188:191], 0
	v_mfma_f32_16x16x32_bf16 v[82:85], v[234:237], v[188:191], 0
	v_mfma_f32_16x16x32_bf16 v[70:73], v[204:207], v[196:199], 0
	v_mfma_f32_16x16x32_bf16 v[66:69], v[234:237], v[196:199], 0
	v_mfma_f32_16x16x32_bf16 v[118:121], v[208:211], v[156:159], v[118:121]
	v_mfma_f32_16x16x32_bf16 v[114:117], v[238:241], v[156:159], v[114:117]
	v_mfma_f32_16x16x32_bf16 v[102:105], v[208:211], v[184:187], v[102:105]
	v_mfma_f32_16x16x32_bf16 v[98:101], v[238:241], v[184:187], v[98:101]
	v_mfma_f32_16x16x32_bf16 v[86:89], v[208:211], v[192:195], v[86:89]
	v_mfma_f32_16x16x32_bf16 v[82:85], v[238:241], v[192:195], v[82:85]
	v_mfma_f32_16x16x32_bf16 v[70:73], v[208:211], v[200:203], v[70:73]
	v_mfma_f32_16x16x32_bf16 v[66:69], v[238:241], v[200:203], v[66:69]
	s_barrier
	s_mov_b32 m0, s2
	ds_read_b128 v[152:155], v233 offset:16384
	ds_read_b128 v[156:159], v233 offset:17408
	ds_read_b128 v[160:163], v233 offset:18432
	ds_read_b128 v[184:187], v233 offset:19456
	ds_read_b128 v[188:191], v233 offset:20480
	ds_read_b128 v[192:195], v233 offset:21504
	ds_read_b128 v[196:199], v233 offset:22528
	ds_read_b128 v[200:203], v233 offset:23552
	global_load_lds_dwordx4 v170, s[98:99]
	s_mov_b32 m0, s3
	s_nop 0
	global_load_lds_dwordx4 v166, s[98:99]
	s_barrier
	s_waitcnt lgkmcnt(0)
	v_mfma_f32_16x16x32_bf16 v[62:65], v[136:139], v[152:155], 0
	v_mfma_f32_16x16x32_bf16 v[58:61], v[144:147], v[152:155], 0
	v_mfma_f32_16x16x32_bf16 v[46:49], v[136:139], v[160:163], 0
	v_mfma_f32_16x16x32_bf16 v[42:45], v[144:147], v[160:163], 0
	v_mfma_f32_16x16x32_bf16 v[30:33], v[136:139], v[188:191], 0
	v_mfma_f32_16x16x32_bf16 v[26:29], v[144:147], v[188:191], 0
	v_mfma_f32_16x16x32_bf16 v[14:17], v[136:139], v[196:199], 0
	v_mfma_f32_16x16x32_bf16 v[10:13], v[144:147], v[196:199], 0
	v_mfma_f32_16x16x32_bf16 v[62:65], v[140:143], v[156:159], v[62:65]
	v_mfma_f32_16x16x32_bf16 v[58:61], v[148:151], v[156:159], v[58:61]
	v_mfma_f32_16x16x32_bf16 v[46:49], v[140:143], v[184:187], v[46:49]
	v_mfma_f32_16x16x32_bf16 v[42:45], v[148:151], v[184:187], v[42:45]
	v_mfma_f32_16x16x32_bf16 v[30:33], v[140:143], v[192:195], v[30:33]
	v_mfma_f32_16x16x32_bf16 v[26:29], v[148:151], v[192:195], v[26:29]
	v_mfma_f32_16x16x32_bf16 v[14:17], v[140:143], v[200:203], v[14:17]
	v_mfma_f32_16x16x32_bf16 v[10:13], v[148:151], v[200:203], v[10:13]
	s_barrier
	s_add_i32 s4, s4, s87
	s_mov_b32 m0, s4
	s_nop 0
	global_load_lds_dwordx4 v242, s[100:101]
	s_add_i32 m0, s4, 0x2000
	s_nop 0
	global_load_lds_dwordx4 v243, s[100:101]
	s_waitcnt vmcnt(6)
	s_barrier
	v_mfma_f32_16x16x32_bf16 v[54:57], v[204:207], v[152:155], 0
	v_mfma_f32_16x16x32_bf16 v[50:53], v[234:237], v[152:155], 0
	v_mfma_f32_16x16x32_bf16 v[38:41], v[204:207], v[160:163], 0
	v_mfma_f32_16x16x32_bf16 v[34:37], v[234:237], v[160:163], 0
	v_mfma_f32_16x16x32_bf16 v[22:25], v[204:207], v[188:191], 0
	v_mfma_f32_16x16x32_bf16 v[18:21], v[234:237], v[188:191], 0
	v_mfma_f32_16x16x32_bf16 v[6:9], v[204:207], v[196:199], 0
	v_mfma_f32_16x16x32_bf16 v[2:5], v[234:237], v[196:199], 0
	v_mfma_f32_16x16x32_bf16 v[54:57], v[208:211], v[156:159], v[54:57]
	v_mfma_f32_16x16x32_bf16 v[50:53], v[238:241], v[156:159], v[50:53]
	v_mfma_f32_16x16x32_bf16 v[38:41], v[208:211], v[184:187], v[38:41]
	v_mfma_f32_16x16x32_bf16 v[34:37], v[238:241], v[184:187], v[34:37]
	v_mfma_f32_16x16x32_bf16 v[22:25], v[208:211], v[192:195], v[22:25]
	v_mfma_f32_16x16x32_bf16 v[18:21], v[238:241], v[192:195], v[18:21]
	v_mfma_f32_16x16x32_bf16 v[6:9], v[208:211], v[200:203], v[6:9]
	v_mfma_f32_16x16x32_bf16 v[2:5], v[238:241], v[200:203], v[2:5]
	s_barrier
; #define PG8_STAGE(bufoff, gbase, voff) do { _Pragma("unroll") for (int _i = 0; _i < 2; ++_i) \
;         __builtin_amdgcn_global_load_lds((const unsigned*)((const char*)(gbase) + (voff)[_i]), (LAS unsigned*)(lds + (bufoff) + ldsw + _i * 8192), 16, 0, 0); } while (0)
; #define PG8_LDA(dst, b, h) do { _Pragma("unroll") for (int m = 0; m < 4; ++m) _Pragma("unroll") for (int k = 0; k < 2; ++k) dst[m][k] = *(const LAS bf16x8*)(lds + PG8_SA(b, h) + aoff + m * 2048 + k * 1024); } while (0)
; #define PG8_LDB(dst, b, h) do { _Pragma("unroll") for (int n = 0; n < 2; ++n) _Pragma("unroll") for (int k = 0; k < 2; ++k) dst[n][k] = *(const LAS bf16x8*)(lds + PG8_SB(b, h) + boff + n * 2048 + k * 1024); } while (0)
; #define PG8_MMA(ai, bj, At, Bt) do { __builtin_amdgcn_s_setprio(1); _Pragma("unroll") for (int m = 0; m < 4; ++m) _Pragma("unroll") for (int n = 0; n < 2; ++n) _Pragma("unroll") for (int k = 0; k < 2; ++k) \
;         acc[ai][bj][m][n] = __builtin_amdgcn_mfma_f32_16x16x32_bf16(Bt[n][k], At[m][k], acc[ai][bj][m][n], 0, 0, 0); __builtin_amdgcn_s_setprio(0); } while (0)
; #define PG8_WAIT_V(n) asm volatile("s_waitcnt vmcnt(" #n ")" ::: "memory")
; #define PG8_WAIT_L(n) asm volatile("s_waitcnt lgkmcnt(" #n ")" ::: "memory")
; #define PG8_BAR __builtin_amdgcn_s_barrier()
; #define PG8_SCHED __builtin_amdgcn_sched_barrier(0)
; __device__ __forceinline__ void gemm_phase(LAS unsigned char* lds, const GemmD& g) {
;     ...
;             PG8_LDB(B0, 1, 0); PG8_SCHED; PG8_LDA(At, 1, 0); PG8_STAGE(PG8_SA(0, 1), a2 + hstep, voffA);
;             PG8_WAIT_L(8); PG8_BAR; PG8_WAIT_L(0); PG8_MMA(0, 0, At, B0); PG8_BAR; PG8_SCHED;
;             PG8_LDB(B1, 1, 1); PG8_STAGE(PG8_SB(1, 0), b3, voffB);
;             PG8_BAR; PG8_WAIT_L(0); PG8_MMA(0, 1, At, B1); PG8_BAR;
;             PG8_LDA(At, 1, 1); PG8_STAGE(PG8_SA(1, 0), a3, voffA);
;             PG8_BAR; PG8_WAIT_L(0); PG8_MMA(1, 0, At, B0); PG8_BAR; PG8_SCHED;
;             PG8_STAGE(PG8_SB(1, 1), b3 + hstep, voffB);
;             PG8_WAIT_V(6); PG8_BAR; PG8_MMA(1, 1, At, B1); PG8_BAR;
;         }
	s_add_i32 s4, 0, 0x18000
	ds_read_b128 v[136:139], v246
	ds_read_b128 v[140:143], v246 offset:1024
	ds_read_b128 v[144:147], v246 offset:2048
	ds_read_b128 v[148:151], v246 offset:3072
	s_mov_b32 m0, s64
	ds_read_b128 v[152:155], v233 offset:32768
	ds_read_b128 v[156:159], v233 offset:33792
	ds_read_b128 v[160:163], v233 offset:34816
	ds_read_b128 v[184:187], v233 offset:35840
	ds_read_b128 v[188:191], v233 offset:36864
	ds_read_b128 v[192:195], v233 offset:37888
	ds_read_b128 v[196:199], v233 offset:38912
	ds_read_b128 v[200:203], v233 offset:39936
	global_load_lds_dwordx4 v174, s[98:99]
	s_mov_b32 m0, s65
	s_nop 0
	global_load_lds_dwordx4 v176, s[98:99]
	s_waitcnt lgkmcnt(8)
	s_barrier
	s_waitcnt lgkmcnt(0)
	v_mfma_f32_16x16x32_bf16 v[126:129], v[136:139], v[152:155], v[126:129]
	v_mfma_f32_16x16x32_bf16 v[122:125], v[144:147], v[152:155], v[122:125]
	v_mfma_f32_16x16x32_bf16 v[110:113], v[136:139], v[160:163], v[110:113]
	v_mfma_f32_16x16x32_bf16 v[106:109], v[144:147], v[160:163], v[106:109]
	v_mfma_f32_16x16x32_bf16 v[94:97], v[136:139], v[188:191], v[94:97]
	v_mfma_f32_16x16x32_bf16 v[90:93], v[144:147], v[188:191], v[90:93]
	v_mfma_f32_16x16x32_bf16 v[78:81], v[136:139], v[196:199], v[78:81]
	v_mfma_f32_16x16x32_bf16 v[74:77], v[144:147], v[196:199], v[74:77]
	v_mfma_f32_16x16x32_bf16 v[126:129], v[140:143], v[156:159], v[126:129]
	v_mfma_f32_16x16x32_bf16 v[122:125], v[148:151], v[156:159], v[122:125]
	v_mfma_f32_16x16x32_bf16 v[110:113], v[140:143], v[184:187], v[110:113]
	v_mfma_f32_16x16x32_bf16 v[106:109], v[148:151], v[184:187], v[106:109]
	v_mfma_f32_16x16x32_bf16 v[94:97], v[140:143], v[192:195], v[94:97]
	v_mfma_f32_16x16x32_bf16 v[90:93], v[148:151], v[192:195], v[90:93]
	v_mfma_f32_16x16x32_bf16 v[78:81], v[140:143], v[200:203], v[78:81]
	v_mfma_f32_16x16x32_bf16 v[74:77], v[148:151], v[200:203], v[74:77]
	s_barrier
	s_add_i32 s6, 0, 0x1c000
	s_add_i32 s4, s4, s87
	ds_read_b128 v[204:207], v247
	ds_read_b128 v[208:211], v247 offset:1024
	ds_read_b128 v[234:237], v247 offset:2048
	ds_read_b128 v[238:241], v247 offset:3072
	s_add_u32 s100, s100, 0x80
	s_addc_u32 s101, s101, 0
	s_mov_b32 m0, s4
	s_nop 0
	global_load_lds_dwordx4 v172, s[100:101]
	s_add_i32 m0, s4, 0x2000
	s_nop 0
	global_load_lds_dwordx4 v168, s[100:101]
	s_barrier
	s_waitcnt lgkmcnt(0)
	v_mfma_f32_16x16x32_bf16 v[118:121], v[204:207], v[152:155], v[118:121]
	v_mfma_f32_16x16x32_bf16 v[114:117], v[234:237], v[152:155], v[114:117]
	v_mfma_f32_16x16x32_bf16 v[102:105], v[204:207], v[160:163], v[102:105]
	v_mfma_f32_16x16x32_bf16 v[98:101], v[234:237], v[160:163], v[98:101]
	v_mfma_f32_16x16x32_bf16 v[86:89], v[204:207], v[188:191], v[86:89]
	v_mfma_f32_16x16x32_bf16 v[82:85], v[234:237], v[188:191], v[82:85]
	v_mfma_f32_16x16x32_bf16 v[70:73], v[204:207], v[196:199], v[70:73]
	v_mfma_f32_16x16x32_bf16 v[66:69], v[234:237], v[196:199], v[66:69]
	v_mfma_f32_16x16x32_bf16 v[118:121], v[208:211], v[156:159], v[118:121]
	v_mfma_f32_16x16x32_bf16 v[114:117], v[238:241], v[156:159], v[114:117]
	v_mfma_f32_16x16x32_bf16 v[102:105], v[208:211], v[184:187], v[102:105]
	v_mfma_f32_16x16x32_bf16 v[98:101], v[238:241], v[184:187], v[98:101]
	v_mfma_f32_16x16x32_bf16 v[86:89], v[208:211], v[192:195], v[86:89]
	v_mfma_f32_16x16x32_bf16 v[82:85], v[238:241], v[192:195], v[82:85]
	v_mfma_f32_16x16x32_bf16 v[70:73], v[208:211], v[200:203], v[70:73]
	v_mfma_f32_16x16x32_bf16 v[66:69], v[238:241], v[200:203], v[66:69]
	s_barrier
	s_mov_b32 m0, s28
	s_add_u32 s98, s98, 0x80
	s_addc_u32 s99, s99, 0
	ds_read_b128 v[152:155], v233 offset:49152
	ds_read_b128 v[156:159], v233 offset:50176
	ds_read_b128 v[160:163], v233 offset:51200
	ds_read_b128 v[184:187], v233 offset:52224
	ds_read_b128 v[188:191], v233 offset:53248
	ds_read_b128 v[192:195], v233 offset:54272
	ds_read_b128 v[196:199], v233 offset:55296
	ds_read_b128 v[200:203], v233 offset:56320
	global_load_lds_dwordx4 v170, s[98:99]
	s_mov_b32 m0, s29
	s_nop 0
	global_load_lds_dwordx4 v166, s[98:99]
	s_barrier
	s_waitcnt lgkmcnt(0)
	v_mfma_f32_16x16x32_bf16 v[62:65], v[136:139], v[152:155], v[62:65]
	v_mfma_f32_16x16x32_bf16 v[58:61], v[144:147], v[152:155], v[58:61]
	v_mfma_f32_16x16x32_bf16 v[46:49], v[136:139], v[160:163], v[46:49]
	v_mfma_f32_16x16x32_bf16 v[42:45], v[144:147], v[160:163], v[42:45]
	v_mfma_f32_16x16x32_bf16 v[30:33], v[136:139], v[188:191], v[30:33]
	v_mfma_f32_16x16x32_bf16 v[26:29], v[144:147], v[188:191], v[26:29]
	v_mfma_f32_16x16x32_bf16 v[14:17], v[136:139], v[196:199], v[14:17]
	v_mfma_f32_16x16x32_bf16 v[10:13], v[144:147], v[196:199], v[10:13]
	v_mfma_f32_16x16x32_bf16 v[62:65], v[140:143], v[156:159], v[62:65]
	v_mfma_f32_16x16x32_bf16 v[58:61], v[148:151], v[156:159], v[58:61]
	v_mfma_f32_16x16x32_bf16 v[46:49], v[140:143], v[184:187], v[46:49]
	v_mfma_f32_16x16x32_bf16 v[42:45], v[148:151], v[184:187], v[42:45]
	v_mfma_f32_16x16x32_bf16 v[30:33], v[140:143], v[192:195], v[30:33]
	v_mfma_f32_16x16x32_bf16 v[26:29], v[148:151], v[192:195], v[26:29]
	v_mfma_f32_16x16x32_bf16 v[14:17], v[140:143], v[200:203], v[14:17]
	v_mfma_f32_16x16x32_bf16 v[10:13], v[148:151], v[200:203], v[10:13]
	s_barrier
	s_add_i32 s4, s6, s87
	s_mov_b32 m0, s4
	s_nop 0
	global_load_lds_dwordx4 v242, s[100:101]
	s_add_i32 m0, s4, 0x2000
	s_nop 0
	global_load_lds_dwordx4 v243, s[100:101]
	s_add_u32 s100, s100, 0x80
	s_addc_u32 s101, s101, 0
	s_mov_b32 s4, s5
	s_waitcnt vmcnt(6)
	s_barrier
	v_mfma_f32_16x16x32_bf16 v[54:57], v[204:207], v[152:155], v[54:57]
	v_mfma_f32_16x16x32_bf16 v[50:53], v[234:237], v[152:155], v[50:53]
	v_mfma_f32_16x16x32_bf16 v[38:41], v[204:207], v[160:163], v[38:41]
	v_mfma_f32_16x16x32_bf16 v[34:37], v[234:237], v[160:163], v[34:37]
	v_mfma_f32_16x16x32_bf16 v[22:25], v[204:207], v[188:191], v[22:25]
	v_mfma_f32_16x16x32_bf16 v[18:21], v[234:237], v[188:191], v[18:21]
	v_mfma_f32_16x16x32_bf16 v[6:9], v[204:207], v[196:199], v[6:9]
	v_mfma_f32_16x16x32_bf16 v[2:5], v[234:237], v[196:199], v[2:5]
	v_mfma_f32_16x16x32_bf16 v[54:57], v[208:211], v[156:159], v[54:57]
	v_mfma_f32_16x16x32_bf16 v[50:53], v[238:241], v[156:159], v[50:53]
	v_mfma_f32_16x16x32_bf16 v[38:41], v[208:211], v[184:187], v[38:41]
	v_mfma_f32_16x16x32_bf16 v[34:37], v[238:241], v[184:187], v[34:37]
	v_mfma_f32_16x16x32_bf16 v[22:25], v[208:211], v[192:195], v[22:25]
	v_mfma_f32_16x16x32_bf16 v[18:21], v[238:241], v[192:195], v[18:21]
	v_mfma_f32_16x16x32_bf16 v[6:9], v[208:211], v[200:203], v[6:9]
	v_mfma_f32_16x16x32_bf16 v[2:5], v[238:241], v[200:203], v[2:5]
	s_barrier
	s_cbranch_vccnz .Lkl_exit

; #define PG8_STAGE(bufoff, gbase, voff) do { _Pragma("unroll") for (int _i = 0; _i < 2; ++_i) \
;         __builtin_amdgcn_global_load_lds((const unsigned*)((const char*)(gbase) + (voff)[_i]), (LAS unsigned*)(lds + (bufoff) + ldsw + _i * 8192), 16, 0, 0); } while (0)
; #define PG8_LDA(dst, b, h) do { _Pragma("unroll") for (int m = 0; m < 4; ++m) _Pragma("unroll") for (int k = 0; k < 2; ++k) dst[m][k] = *(const LAS bf16x8*)(lds + PG8_SA(b, h) + aoff + m * 2048 + k * 1024); } while (0)
; #define PG8_LDB(dst, b, h) do { _Pragma("unroll") for (int n = 0; n < 2; ++n) _Pragma("unroll") for (int k = 0; k < 2; ++k) dst[n][k] = *(const LAS bf16x8*)(lds + PG8_SB(b, h) + boff + n * 2048 + k * 1024); } while (0)
; #define PG8_MMA(ai, bj, At, Bt) do { __builtin_amdgcn_s_setprio(1); _Pragma("unroll") for (int m = 0; m < 4; ++m) _Pragma("unroll") for (int n = 0; n < 2; ++n) _Pragma("unroll") for (int k = 0; k < 2; ++k) \
;         acc[ai][bj][m][n] = __builtin_amdgcn_mfma_f32_16x16x32_bf16(Bt[n][k], At[m][k], acc[ai][bj][m][n], 0, 0, 0); __builtin_amdgcn_s_setprio(0); } while (0)
; #define PG8_WAIT_V(n) asm volatile("s_waitcnt vmcnt(" #n ")" ::: "memory")
; #define PG8_WAIT_L(n) asm volatile("s_waitcnt lgkmcnt(" #n ")" ::: "memory")
; #define PG8_BAR __builtin_amdgcn_s_barrier()
; #define PG8_SCHED __builtin_amdgcn_sched_barrier(0)
; __device__ __forceinline__ void gemm_phase(LAS unsigned char* lds, const GemmD& g) {
;     ...
;             PG8_WAIT_L(8); PG8_BAR; PG8_WAIT_L(0); PG8_MMA(0, 0, At, B0); PG8_BAR; PG8_SCHED;
;             PG8_LDB(B1, 0, 1); PG8_STAGE(PG8_SB(0, 0), b2, voffB);
;             PG8_BAR; PG8_WAIT_L(0); PG8_MMA(0, 1, At, B1); PG8_BAR;
;             PG8_LDA(At, 0, 1); PG8_STAGE(PG8_SA(0, 0), a2, voffA);
;             PG8_BAR; PG8_WAIT_L(0); PG8_MMA(1, 0, At, B0); PG8_BAR; PG8_SCHED;
;             PG8_STAGE(PG8_SB(0, 1), b2 + hstep, voffB);
;             PG8_WAIT_V(6); PG8_BAR; PG8_MMA(1, 1, At, B1); PG8_BAR;
;             PG8_LDB(B0, 1, 0); PG8_SCHED; PG8_LDA(At, 1, 0); PG8_STAGE(PG8_SA(0, 1), a2 + hstep, voffA);
.Lkl_ptr_done:
	s_waitcnt lgkmcnt(8)
	s_barrier
	s_waitcnt lgkmcnt(0)
	v_mfma_f32_16x16x32_bf16 v[126:129], v[136:139], v[152:155], v[126:129]
	v_mfma_f32_16x16x32_bf16 v[122:125], v[144:147], v[152:155], v[122:125]
	v_mfma_f32_16x16x32_bf16 v[110:113], v[136:139], v[160:163], v[110:113]
	v_mfma_f32_16x16x32_bf16 v[106:109], v[144:147], v[160:163], v[106:109]
	v_mfma_f32_16x16x32_bf16 v[94:97], v[136:139], v[188:191], v[94:97]
	v_mfma_f32_16x16x32_bf16 v[90:93], v[144:147], v[188:191], v[90:93]
	v_mfma_f32_16x16x32_bf16 v[78:81], v[136:139], v[196:199], v[78:81]
	v_mfma_f32_16x16x32_bf16 v[74:77], v[144:147], v[196:199], v[74:77]
	v_mfma_f32_16x16x32_bf16 v[126:129], v[140:143], v[156:159], v[126:129]
	v_mfma_f32_16x16x32_bf16 v[122:125], v[148:151], v[156:159], v[122:125]
	v_mfma_f32_16x16x32_bf16 v[110:113], v[140:143], v[184:187], v[110:113]
	v_mfma_f32_16x16x32_bf16 v[106:109], v[148:151], v[184:187], v[106:109]
	v_mfma_f32_16x16x32_bf16 v[94:97], v[140:143], v[192:195], v[94:97]
	v_mfma_f32_16x16x32_bf16 v[90:93], v[148:151], v[192:195], v[90:93]
	v_mfma_f32_16x16x32_bf16 v[78:81], v[140:143], v[200:203], v[78:81]
	v_mfma_f32_16x16x32_bf16 v[74:77], v[148:151], v[200:203], v[74:77]
	s_barrier
	s_add_i32 s4, 0, 0x14000
	s_add_i32 s6, s6, s87
	s_mov_b32 m0, s6
	ds_read_b128 v[204:207], v245
	ds_read_b128 v[208:211], v245 offset:1024
	ds_read_b128 v[234:237], v245 offset:2048
	ds_read_b128 v[238:241], v245 offset:3072
	global_load_lds_dwordx4 v172, s[100:101]
	s_add_i32 m0, s6, 0x2000
	s_nop 0
	global_load_lds_dwordx4 v168, s[100:101]
	s_barrier
	s_waitcnt lgkmcnt(0)
	v_mfma_f32_16x16x32_bf16 v[118:121], v[204:207], v[152:155], v[118:121]
	v_mfma_f32_16x16x32_bf16 v[114:117], v[234:237], v[152:155], v[114:117]
	v_mfma_f32_16x16x32_bf16 v[102:105], v[204:207], v[160:163], v[102:105]
	v_mfma_f32_16x16x32_bf16 v[98:101], v[234:237], v[160:163], v[98:101]
	v_mfma_f32_16x16x32_bf16 v[86:89], v[204:207], v[188:191], v[86:89]
	v_mfma_f32_16x16x32_bf16 v[82:85], v[234:237], v[188:191], v[82:85]
	v_mfma_f32_16x16x32_bf16 v[70:73], v[204:207], v[196:199], v[70:73]
	v_mfma_f32_16x16x32_bf16 v[66:69], v[234:237], v[196:199], v[66:69]
	v_mfma_f32_16x16x32_bf16 v[118:121], v[208:211], v[156:159], v[118:121]
	v_mfma_f32_16x16x32_bf16 v[114:117], v[238:241], v[156:159], v[114:117]
	v_mfma_f32_16x16x32_bf16 v[102:105], v[208:211], v[184:187], v[102:105]
	v_mfma_f32_16x16x32_bf16 v[98:101], v[238:241], v[184:187], v[98:101]
	v_mfma_f32_16x16x32_bf16 v[86:89], v[208:211], v[192:195], v[86:89]
	v_mfma_f32_16x16x32_bf16 v[82:85], v[238:241], v[192:195], v[82:85]
	v_mfma_f32_16x16x32_bf16 v[70:73], v[208:211], v[200:203], v[70:73]
	v_mfma_f32_16x16x32_bf16 v[66:69], v[238:241], v[200:203], v[66:69]
	s_barrier
	s_mov_b32 m0, s2
	ds_read_b128 v[152:155], v233 offset:16384
	ds_read_b128 v[156:159], v233 offset:17408
	ds_read_b128 v[160:163], v233 offset:18432
	ds_read_b128 v[184:187], v233 offset:19456
	ds_read_b128 v[188:191], v233 offset:20480
	ds_read_b128 v[192:195], v233 offset:21504
	ds_read_b128 v[196:199], v233 offset:22528
	ds_read_b128 v[200:203], v233 offset:23552
	global_load_lds_dwordx4 v170, s[98:99]
	s_mov_b32 m0, s3
	s_nop 0
	global_load_lds_dwordx4 v166, s[98:99]
	s_barrier
	s_waitcnt lgkmcnt(0)
	v_mfma_f32_16x16x32_bf16 v[62:65], v[136:139], v[152:155], v[62:65]
	v_mfma_f32_16x16x32_bf16 v[58:61], v[144:147], v[152:155], v[58:61]
	v_mfma_f32_16x16x32_bf16 v[46:49], v[136:139], v[160:163], v[46:49]
	v_mfma_f32_16x16x32_bf16 v[42:45], v[144:147], v[160:163], v[42:45]
	v_mfma_f32_16x16x32_bf16 v[30:33], v[136:139], v[188:191], v[30:33]
	v_mfma_f32_16x16x32_bf16 v[26:29], v[144:147], v[188:191], v[26:29]
	v_mfma_f32_16x16x32_bf16 v[14:17], v[136:139], v[196:199], v[14:17]
	v_mfma_f32_16x16x32_bf16 v[10:13], v[144:147], v[196:199], v[10:13]
	v_mfma_f32_16x16x32_bf16 v[62:65], v[140:143], v[156:159], v[62:65]
	v_mfma_f32_16x16x32_bf16 v[58:61], v[148:151], v[156:159], v[58:61]
	v_mfma_f32_16x16x32_bf16 v[46:49], v[140:143], v[184:187], v[46:49]
	v_mfma_f32_16x16x32_bf16 v[42:45], v[148:151], v[184:187], v[42:45]
	v_mfma_f32_16x16x32_bf16 v[30:33], v[140:143], v[192:195], v[30:33]
	v_mfma_f32_16x16x32_bf16 v[26:29], v[148:151], v[192:195], v[26:29]
	v_mfma_f32_16x16x32_bf16 v[14:17], v[140:143], v[200:203], v[14:17]
	v_mfma_f32_16x16x32_bf16 v[10:13], v[148:151], v[200:203], v[10:13]
	s_barrier
	s_add_i32 s4, s4, s87
	s_mov_b32 m0, s4
	s_nop 0
	global_load_lds_dwordx4 v242, s[100:101]
	s_add_i32 m0, s4, 0x2000
	s_nop 0
	global_load_lds_dwordx4 v243, s[100:101]
	s_waitcnt vmcnt(6)
	s_barrier
	v_mfma_f32_16x16x32_bf16 v[54:57], v[204:207], v[152:155], v[54:57]
	v_mfma_f32_16x16x32_bf16 v[50:53], v[234:237], v[152:155], v[50:53]
	v_mfma_f32_16x16x32_bf16 v[38:41], v[204:207], v[160:163], v[38:41]
	v_mfma_f32_16x16x32_bf16 v[34:37], v[234:237], v[160:163], v[34:37]
	v_mfma_f32_16x16x32_bf16 v[22:25], v[204:207], v[188:191], v[22:25]
	v_mfma_f32_16x16x32_bf16 v[18:21], v[234:237], v[188:191], v[18:21]
	v_mfma_f32_16x16x32_bf16 v[6:9], v[204:207], v[196:199], v[6:9]
	v_mfma_f32_16x16x32_bf16 v[2:5], v[234:237], v[196:199], v[2:5]
	v_mfma_f32_16x16x32_bf16 v[54:57], v[208:211], v[156:159], v[54:57]
	v_mfma_f32_16x16x32_bf16 v[50:53], v[238:241], v[156:159], v[50:53]
	v_mfma_f32_16x16x32_bf16 v[38:41], v[208:211], v[184:187], v[38:41]
	v_mfma_f32_16x16x32_bf16 v[34:37], v[238:241], v[184:187], v[34:37]
	v_mfma_f32_16x16x32_bf16 v[22:25], v[208:211], v[192:195], v[22:25]
	v_mfma_f32_16x16x32_bf16 v[18:21], v[238:241], v[192:195], v[18:21]
	v_mfma_f32_16x16x32_bf16 v[6:9], v[208:211], v[200:203], v[6:9]
	v_mfma_f32_16x16x32_bf16 v[2:5], v[238:241], v[200:203], v[2:5]
	s_barrier
; #define PG8_STAGE(bufoff, gbase, voff) do { _Pragma("unroll") for (int _i = 0; _i < 2; ++_i) \
;         __builtin_amdgcn_global_load_lds((const unsigned*)((const char*)(gbase) + (voff)[_i]), (LAS unsigned*)(lds + (bufoff) + ldsw + _i * 8192), 16, 0, 0); } while (0)
; #define PG8_LDA(dst, b, h) do { _Pragma("unroll") for (int m = 0; m < 4; ++m) _Pragma("unroll") for (int k = 0; k < 2; ++k) dst[m][k] = *(const LAS bf16x8*)(lds + PG8_SA(b, h) + aoff + m * 2048 + k * 1024); } while (0)
; #define PG8_LDB(dst, b, h) do { _Pragma("unroll") for (int n = 0; n < 2; ++n) _Pragma("unroll") for (int k = 0; k < 2; ++k) dst[n][k] = *(const LAS bf16x8*)(lds + PG8_SB(b, h) + boff + n * 2048 + k * 1024); } while (0)
; #define PG8_MMA(ai, bj, At, Bt) do { __builtin_amdgcn_s_setprio(1); _Pragma("unroll") for (int m = 0; m < 4; ++m) _Pragma("unroll") for (int n = 0; n < 2; ++n) _Pragma("unroll") for (int k = 0; k < 2; ++k) \
;         acc[ai][bj][m][n] = __builtin_amdgcn_mfma_f32_16x16x32_bf16(Bt[n][k], At[m][k], acc[ai][bj][m][n], 0, 0, 0); __builtin_amdgcn_s_setprio(0); } while (0)
; #define PG8_WAIT_V(n) asm volatile("s_waitcnt vmcnt(" #n ")" ::: "memory")
; #define PG8_WAIT_L(n) asm volatile("s_waitcnt lgkmcnt(" #n ")" ::: "memory")
; #define PG8_BAR __builtin_amdgcn_s_barrier()
; #define PG8_SCHED __builtin_amdgcn_sched_barrier(0)
; __device__ __forceinline__ void gemm_phase(LAS unsigned char* lds, const GemmD& g) {
;     ...
;             PG8_LDB(B0, 1, 0); PG8_SCHED; PG8_LDA(At, 1, 0); PG8_STAGE(PG8_SA(0, 1), a2 + hstep, voffA);
;             PG8_WAIT_L(8); PG8_BAR; PG8_WAIT_L(0); PG8_MMA(0, 0, At, B0); PG8_BAR; PG8_SCHED;
;             PG8_LDB(B1, 1, 1); PG8_STAGE(PG8_SB(1, 0), b3, voffB);
;             PG8_BAR; PG8_WAIT_L(0); PG8_MMA(0, 1, At, B1); PG8_BAR;
;             PG8_LDA(At, 1, 1); PG8_STAGE(PG8_SA(1, 0), a3, voffA);
;             PG8_BAR; PG8_WAIT_L(0); PG8_MMA(1, 0, At, B0); PG8_BAR; PG8_SCHED;
;             PG8_STAGE(PG8_SB(1, 1), b3 + hstep, voffB);
;             PG8_WAIT_V(6); PG8_BAR; PG8_MMA(1, 1, At, B1); PG8_BAR;
;         }
;         gemm_epilogue(g, acc, cur, wr, wc, fr, fq);
;         if (!has_next) break;
	s_add_i32 s4, 0, 0x18000
	ds_read_b128 v[136:139], v246
	ds_read_b128 v[140:143], v246 offset:1024
	ds_read_b128 v[144:147], v246 offset:2048
	ds_read_b128 v[148:151], v246 offset:3072
	s_mov_b32 m0, s64
	ds_read_b128 v[152:155], v233 offset:32768
	ds_read_b128 v[156:159], v233 offset:33792
	ds_read_b128 v[160:163], v233 offset:34816
	ds_read_b128 v[184:187], v233 offset:35840
	ds_read_b128 v[188:191], v233 offset:36864
	ds_read_b128 v[192:195], v233 offset:37888
	ds_read_b128 v[196:199], v233 offset:38912
	ds_read_b128 v[200:203], v233 offset:39936
	global_load_lds_dwordx4 v174, s[98:99]
	s_mov_b32 m0, s65
	s_nop 0
	global_load_lds_dwordx4 v176, s[98:99]
	s_waitcnt lgkmcnt(8)
	s_barrier
	s_waitcnt lgkmcnt(0)
	v_mfma_f32_16x16x32_bf16 v[126:129], v[136:139], v[152:155], v[126:129]
	v_mfma_f32_16x16x32_bf16 v[122:125], v[144:147], v[152:155], v[122:125]
	v_mfma_f32_16x16x32_bf16 v[110:113], v[136:139], v[160:163], v[110:113]
	v_mfma_f32_16x16x32_bf16 v[106:109], v[144:147], v[160:163], v[106:109]
	v_mfma_f32_16x16x32_bf16 v[94:97], v[136:139], v[188:191], v[94:97]
	v_mfma_f32_16x16x32_bf16 v[90:93], v[144:147], v[188:191], v[90:93]
	v_mfma_f32_16x16x32_bf16 v[78:81], v[136:139], v[196:199], v[78:81]
	v_mfma_f32_16x16x32_bf16 v[74:77], v[144:147], v[196:199], v[74:77]
	v_mfma_f32_16x16x32_bf16 v[126:129], v[140:143], v[156:159], v[126:129]
	v_mfma_f32_16x16x32_bf16 v[122:125], v[148:151], v[156:159], v[122:125]
	v_mfma_f32_16x16x32_bf16 v[110:113], v[140:143], v[184:187], v[110:113]
	v_mfma_f32_16x16x32_bf16 v[106:109], v[148:151], v[184:187], v[106:109]
	v_mfma_f32_16x16x32_bf16 v[94:97], v[140:143], v[192:195], v[94:97]
	v_mfma_f32_16x16x32_bf16 v[90:93], v[148:151], v[192:195], v[90:93]
	v_mfma_f32_16x16x32_bf16 v[78:81], v[140:143], v[200:203], v[78:81]
	v_mfma_f32_16x16x32_bf16 v[74:77], v[148:151], v[200:203], v[74:77]
	s_barrier
	s_add_i32 s6, 0, 0x1c000
	s_add_i32 s4, s4, s87
	ds_read_b128 v[204:207], v247
	ds_read_b128 v[208:211], v247 offset:1024
	ds_read_b128 v[234:237], v247 offset:2048
	ds_read_b128 v[238:241], v247 offset:3072
	s_add_u32 s100, s100, 0x80
	s_addc_u32 s101, s101, 0
	s_mov_b32 m0, s4
	s_nop 0
	global_load_lds_dwordx4 v172, s[100:101]
	s_add_i32 m0, s4, 0x2000
	s_nop 0
	global_load_lds_dwordx4 v168, s[100:101]
	s_barrier
	s_waitcnt lgkmcnt(0)
	v_mfma_f32_16x16x32_bf16 v[118:121], v[204:207], v[152:155], v[118:121]
	v_mfma_f32_16x16x32_bf16 v[114:117], v[234:237], v[152:155], v[114:117]
	v_mfma_f32_16x16x32_bf16 v[102:105], v[204:207], v[160:163], v[102:105]
	v_mfma_f32_16x16x32_bf16 v[98:101], v[234:237], v[160:163], v[98:101]
	v_mfma_f32_16x16x32_bf16 v[86:89], v[204:207], v[188:191], v[86:89]
	v_mfma_f32_16x16x32_bf16 v[82:85], v[234:237], v[188:191], v[82:85]
	v_mfma_f32_16x16x32_bf16 v[70:73], v[204:207], v[196:199], v[70:73]
	v_mfma_f32_16x16x32_bf16 v[66:69], v[234:237], v[196:199], v[66:69]
	v_mfma_f32_16x16x32_bf16 v[118:121], v[208:211], v[156:159], v[118:121]
	v_mfma_f32_16x16x32_bf16 v[114:117], v[238:241], v[156:159], v[114:117]
	v_mfma_f32_16x16x32_bf16 v[102:105], v[208:211], v[184:187], v[102:105]
	v_mfma_f32_16x16x32_bf16 v[98:101], v[238:241], v[184:187], v[98:101]
	v_mfma_f32_16x16x32_bf16 v[86:89], v[208:211], v[192:195], v[86:89]
	v_mfma_f32_16x16x32_bf16 v[82:85], v[238:241], v[192:195], v[82:85]
	v_mfma_f32_16x16x32_bf16 v[70:73], v[208:211], v[200:203], v[70:73]
	v_mfma_f32_16x16x32_bf16 v[66:69], v[238:241], v[200:203], v[66:69]
	s_barrier
	s_mov_b32 m0, s28
	s_add_u32 s98, s98, 0x80
	s_addc_u32 s99, s99, 0
	ds_read_b128 v[152:155], v233 offset:49152
	ds_read_b128 v[156:159], v233 offset:50176
	ds_read_b128 v[160:163], v233 offset:51200
	ds_read_b128 v[184:187], v233 offset:52224
	ds_read_b128 v[188:191], v233 offset:53248
	ds_read_b128 v[192:195], v233 offset:54272
	ds_read_b128 v[196:199], v233 offset:55296
	ds_read_b128 v[200:203], v233 offset:56320
	global_load_lds_dwordx4 v170, s[98:99]
	s_mov_b32 m0, s29
	s_nop 0
	global_load_lds_dwordx4 v166, s[98:99]
	s_barrier
	s_waitcnt lgkmcnt(0)
	v_mfma_f32_16x16x32_bf16 v[62:65], v[136:139], v[152:155], v[62:65]
	v_mfma_f32_16x16x32_bf16 v[58:61], v[144:147], v[152:155], v[58:61]
	v_mfma_f32_16x16x32_bf16 v[46:49], v[136:139], v[160:163], v[46:49]
	v_mfma_f32_16x16x32_bf16 v[42:45], v[144:147], v[160:163], v[42:45]
	v_mfma_f32_16x16x32_bf16 v[30:33], v[136:139], v[188:191], v[30:33]
	v_mfma_f32_16x16x32_bf16 v[26:29], v[144:147], v[188:191], v[26:29]
	v_mfma_f32_16x16x32_bf16 v[14:17], v[136:139], v[196:199], v[14:17]
	v_mfma_f32_16x16x32_bf16 v[10:13], v[144:147], v[196:199], v[10:13]
	v_mfma_f32_16x16x32_bf16 v[62:65], v[140:143], v[156:159], v[62:65]
	v_mfma_f32_16x16x32_bf16 v[58:61], v[148:151], v[156:159], v[58:61]
	v_mfma_f32_16x16x32_bf16 v[46:49], v[140:143], v[184:187], v[46:49]
	v_mfma_f32_16x16x32_bf16 v[42:45], v[148:151], v[184:187], v[42:45]
	v_mfma_f32_16x16x32_bf16 v[30:33], v[140:143], v[192:195], v[30:33]
	v_mfma_f32_16x16x32_bf16 v[26:29], v[148:151], v[192:195], v[26:29]
	v_mfma_f32_16x16x32_bf16 v[14:17], v[140:143], v[200:203], v[14:17]
	v_mfma_f32_16x16x32_bf16 v[10:13], v[148:151], v[200:203], v[10:13]
	s_barrier
	s_add_i32 s4, s6, s87
	s_mov_b32 m0, s4
	s_nop 0
	global_load_lds_dwordx4 v242, s[100:101]
	s_add_i32 m0, s4, 0x2000
	s_nop 0
	global_load_lds_dwordx4 v243, s[100:101]
	s_add_u32 s100, s100, 0x80
	s_addc_u32 s101, s101, 0
	s_mov_b32 s4, s5
	s_waitcnt vmcnt(6)
	s_barrier
	v_mfma_f32_16x16x32_bf16 v[54:57], v[204:207], v[152:155], v[54:57]
	v_mfma_f32_16x16x32_bf16 v[50:53], v[234:237], v[152:155], v[50:53]
	v_mfma_f32_16x16x32_bf16 v[38:41], v[204:207], v[160:163], v[38:41]
	v_mfma_f32_16x16x32_bf16 v[34:37], v[234:237], v[160:163], v[34:37]
	v_mfma_f32_16x16x32_bf16 v[22:25], v[204:207], v[188:191], v[22:25]
	v_mfma_f32_16x16x32_bf16 v[18:21], v[234:237], v[188:191], v[18:21]
	v_mfma_f32_16x16x32_bf16 v[6:9], v[204:207], v[196:199], v[6:9]
	v_mfma_f32_16x16x32_bf16 v[2:5], v[234:237], v[196:199], v[2:5]
	v_mfma_f32_16x16x32_bf16 v[54:57], v[208:211], v[156:159], v[54:57]
	v_mfma_f32_16x16x32_bf16 v[50:53], v[238:241], v[156:159], v[50:53]
	v_mfma_f32_16x16x32_bf16 v[38:41], v[208:211], v[184:187], v[38:41]
	v_mfma_f32_16x16x32_bf16 v[34:37], v[238:241], v[184:187], v[34:37]
	v_mfma_f32_16x16x32_bf16 v[22:25], v[208:211], v[192:195], v[22:25]
	v_mfma_f32_16x16x32_bf16 v[18:21], v[238:241], v[192:195], v[18:21]
	v_mfma_f32_16x16x32_bf16 v[6:9], v[208:211], v[200:203], v[6:9]
	v_mfma_f32_16x16x32_bf16 v[2:5], v[238:241], v[200:203], v[2:5]
	s_barrier
	s_cbranch_vccz .LBB0_145
.Lkl_exit:
	v_lshl_add_u32 v184, s56, 8, v228
	s_cmp_lt_i32 s66, 0
	s_mov_b64 s[4:5], -1
	s_cbranch_scc0 .LBB0_704
